# prologue weight-transpose: 16 LDS transposed reads issued together with counted lgkmcnt waits (on v38)
# speedup vs baseline: 1.0277x; 1.0277x over previous
; __device__ __forceinline__ unsigned cvt_pk_bf16(float lo, float hi) { unsigned r; asm volatile("v_cvt_pk_bf16_f32 %0, %1, %2" : "=v"(r) : "v"(lo), "v"(hi)); return r; }
; #define LAS __attribute__((address_space(3)))
; #define LDS_WAIT() asm volatile("s_waitcnt lgkmcnt(0)" ::: "memory")
; __device__ __forceinline__ void tr_store(const float (&v)[32], const TrDesc& d, LAS float* scr, int lane) {
; #pragma unroll
;     for (int i = 0; i < 32; ++i) { const int kk = 2 * i + (lane >> 5); float x = v[i]; if (d.gk) x *= d.gk[d.k0 + kk]; scr[kk * 33 + (lane & 31)] = x; }
;     LDS_WAIT();
;     const int c = lane & 7;
; #pragma unroll
;     for (int j = 0; j < 4; ++j) { const int n = (lane >> 3) + 8 * j; const LAS float* s = scr + (8 * c) * 33 + n;
;         v4u o; o.x = pg8::cvt_pk_bf16(s[0 * 33], s[1 * 33]); o.y = pg8::cvt_pk_bf16(s[2 * 33], s[3 * 33]); o.z = pg8::cvt_pk_bf16(s[4 * 33], s[5 * 33]); o.w = pg8::cvt_pk_bf16(s[6 * 33], s[7 * 33]);
;         *(v4u*)(d.WT + (size_t)(d.n0 + n) * (d.K + WPAD) + d.k0 + 8 * c) = o; }
;     LDS_WAIT();
; __global__ void __launch_bounds__(NWAVES * 64, 2) hybrid_fwd(Args args) {
;     ...
;                 for (; it < I_ALL; it += TSTEP) {
;                     { const int q = it + 2 * TSTEP < I_ALL ? it + 2 * TSTEP : it; TR_DECODE(q, d2); }
;                     tr_load(vc, d2, lane);
;                     tr_store(va, d0, scr, lane);
; #pragma unroll
;                     for (int i = 0; i < 32; ++i) { va[i] = vb[i]; vb[i] = vc[i]; }
;                     d0 = d1; d1 = d2;
;                 }
.LBB0_552:
	ds_write_b32 v73, v0 offset:8184
	s_waitcnt lgkmcnt(0)
	ds_read2_b32 v[190:191], v69 offset1:33
	ds_read2_b32 v[192:193], v69 offset0:66 offset1:99
	ds_read2_b32 v[194:195], v69 offset0:132 offset1:165
	ds_read2_b32 v[196:197], v69 offset0:198 offset1:231
	ds_read2_b32 v[198:199], v69 offset0:8 offset1:41
	ds_read2_b32 v[200:201], v69 offset0:74 offset1:107
	ds_read2_b32 v[202:203], v69 offset0:140 offset1:173
	ds_read2_b32 v[204:205], v69 offset0:206 offset1:239
	ds_read2_b32 v[206:207], v69 offset0:16 offset1:49
	ds_read2_b32 v[208:209], v69 offset0:82 offset1:115
	ds_read2_b32 v[210:211], v69 offset0:148 offset1:181
	ds_read2_b32 v[212:213], v69 offset0:214 offset1:247
	ds_read2_b32 v[214:215], v69 offset0:24 offset1:57
	ds_read2_b32 v[216:217], v69 offset0:90 offset1:123
	ds_read2_b32 v[218:219], v69 offset0:156 offset1:189
	ds_read2_b32 v[220:221], v69 offset0:222 offset1:255
	v_add_u32_e32 v6, s2, v68
	v_mul_hi_i32_i24_e32 v7, s4, v6
	v_mul_i32_i24_e32 v6, s4, v6
	s_waitcnt lgkmcnt(15)
	v_cvt_pk_bf16_f32 v0, v190, v191
	s_lshl_b64 s[6:7], s[16:17], 1
	v_lshl_add_u64 v[6:7], v[6:7], 1, s[0:1]
	s_waitcnt lgkmcnt(14)
	v_cvt_pk_bf16_f32 v1, v192, v193
	v_mov_b32_e32 v35, v129
	v_lshl_add_u64 v[6:7], v[6:7], 0, s[6:7]
	s_waitcnt lgkmcnt(13)
	v_cvt_pk_bf16_f32 v2, v194, v195
	s_waitcnt lgkmcnt(12)
	v_cvt_pk_bf16_f32 v3, v196, v197
	v_lshl_add_u64 v[6:7], v[6:7], 0, v[34:35]
	global_store_dwordx4 v[6:7], v[0:3], off sc1
	s_mov_b32 s16, s5
	s_waitcnt vmcnt(54)
	v_mov_b32_e32 v14, v74
	s_waitcnt lgkmcnt(11)
	v_cvt_pk_bf16_f32 v0, v198, v199
	s_waitcnt lgkmcnt(10)
	v_cvt_pk_bf16_f32 v1, v200, v201
	s_waitcnt lgkmcnt(9)
	v_cvt_pk_bf16_f32 v2, v202, v203
	v_add_u32_e32 v3, s2, v70
	v_mul_hi_i32_i24_e32 v7, s4, v3
	v_mul_i32_i24_e32 v6, s4, v3
	v_lshl_add_u64 v[6:7], v[6:7], 1, s[0:1]
	v_lshl_add_u64 v[6:7], v[6:7], 0, s[6:7]
	s_waitcnt lgkmcnt(8)
	v_cvt_pk_bf16_f32 v3, v204, v205
	v_lshl_add_u64 v[6:7], v[6:7], 0, v[34:35]
	global_store_dwordx4 v[6:7], v[0:3], off sc1
	v_mov_b32_e32 v15, v59
	s_waitcnt vmcnt(18)
	v_mov_b32_e32 v59, v106
	s_waitcnt lgkmcnt(7)
	v_cvt_pk_bf16_f32 v0, v206, v207
	s_waitcnt lgkmcnt(6)
	v_cvt_pk_bf16_f32 v1, v208, v209
	s_waitcnt lgkmcnt(5)
	v_cvt_pk_bf16_f32 v2, v210, v211
	v_add_u32_e32 v3, s2, v71
	v_mul_hi_i32_i24_e32 v7, s4, v3
	v_mul_i32_i24_e32 v6, s4, v3
	v_lshl_add_u64 v[6:7], v[6:7], 1, s[0:1]
	v_lshl_add_u64 v[6:7], v[6:7], 0, s[6:7]
	s_waitcnt lgkmcnt(4)
	v_cvt_pk_bf16_f32 v3, v212, v213
	v_lshl_add_u64 v[6:7], v[6:7], 0, v[34:35]
	global_store_dwordx4 v[6:7], v[0:3], off sc1
	v_mov_b32_e32 v74, v105
	v_mov_b32_e32 v13, v46
	s_waitcnt lgkmcnt(3)
	v_cvt_pk_bf16_f32 v0, v214, v215
	v_add_u32_e32 v4, s2, v72
	v_mul_hi_i32_i24_e32 v5, s4, v4
	v_mul_i32_i24_e32 v4, s4, v4
	v_lshl_add_u64 v[4:5], v[4:5], 1, s[0:1]
	v_lshl_add_u64 v[4:5], v[4:5], 0, s[6:7]
	s_waitcnt lgkmcnt(2)
	v_cvt_pk_bf16_f32 v1, v216, v217
	v_lshl_add_u64 v[4:5], v[4:5], 0, v[34:35]
	s_waitcnt lgkmcnt(1)
	v_cvt_pk_bf16_f32 v2, v218, v219
	s_waitcnt lgkmcnt(0)
	v_cvt_pk_bf16_f32 v3, v220, v221
	global_store_dwordx4 v[4:5], v[0:3], off sc1
	s_waitcnt lgkmcnt(0)
	s_add_i32 s2, s93, s94
	s_mov_b64 s[4:5], s[10:11]
	v_mov_b32_e32 v46, v104
	v_mov_b32_e32 v12, v48
	v_mov_b32_e32 v48, v103
	v_mov_b32_e32 v11, v47
	v_mov_b32_e32 v47, v102
	v_mov_b32_e32 v10, v49
	v_mov_b32_e32 v49, v101
	v_mov_b32_e32 v9, v50
	v_mov_b32_e32 v50, v100
	v_mov_b32_e32 v8, v51
	v_mov_b32_e32 v51, v99
	v_mov_b32_e32 v7, v52
	v_mov_b32_e32 v52, v82
	s_cmpk_lt_i32 s2, 0x2b00
	v_mov_b32_e32 v6, v53
	v_mov_b32_e32 v53, v81
	v_mov_b32_e32 v5, v54
	v_mov_b32_e32 v54, v80
	v_mov_b32_e32 v4, v55
	v_mov_b32_e32 v55, v79
	v_mov_b32_e32 v3, v56
	v_mov_b32_e32 v56, v78
	v_mov_b32_e32 v2, v57
	v_mov_b32_e32 v57, v77
	v_mov_b32_e32 v1, v58
	v_mov_b32_e32 v58, v76
	v_mov_b32_e32 v0, v67
	v_mov_b32_e32 v67, v75
	v_mov_b32_e32 v16, v45
	s_waitcnt vmcnt(19)
	v_mov_b32_e32 v45, v83
	v_mov_b32_e32 v17, v44
	s_waitcnt vmcnt(18)
	v_mov_b32_e32 v44, v84
	v_mov_b32_e32 v18, v43
	s_waitcnt vmcnt(17)
	v_mov_b32_e32 v43, v85
	v_mov_b32_e32 v19, v42
	s_waitcnt vmcnt(16)
	v_mov_b32_e32 v42, v86
	v_mov_b32_e32 v20, v41
	s_waitcnt vmcnt(15)
	v_mov_b32_e32 v41, v87
	v_mov_b32_e32 v21, v40
	s_waitcnt vmcnt(14)
	v_mov_b32_e32 v40, v88
	v_mov_b32_e32 v22, v39
	s_waitcnt vmcnt(13)
	v_mov_b32_e32 v39, v89
	v_mov_b32_e32 v23, v38
	s_waitcnt vmcnt(12)
	v_mov_b32_e32 v38, v90
	v_mov_b32_e32 v24, v37
	s_waitcnt vmcnt(11)
	v_mov_b32_e32 v37, v91
	v_mov_b32_e32 v25, v66
	s_waitcnt vmcnt(10)
	v_mov_b32_e32 v66, v92
	v_mov_b32_e32 v26, v65
	s_waitcnt vmcnt(9)
	v_mov_b32_e32 v65, v93
	v_mov_b32_e32 v27, v64
	s_waitcnt vmcnt(8)
	v_mov_b32_e32 v64, v94
	v_mov_b32_e32 v28, v63
	s_waitcnt vmcnt(7)
	v_mov_b32_e32 v63, v95
	v_mov_b32_e32 v29, v62
	s_waitcnt vmcnt(6)
	v_mov_b32_e32 v62, v96
	v_mov_b32_e32 v30, v61
	s_waitcnt vmcnt(5)
	v_mov_b32_e32 v61, v97
	v_mov_b32_e32 v31, v60
	s_waitcnt vmcnt(4)
	v_mov_b32_e32 v60, v98
	s_mov_b32 s2, s18
	s_mov_b64 s[14:15], s[12:13]
	s_mov_b64 s[0:1], s[8:9]
	s_mov_b32 s18, s74
	s_mov_b32 s5, s19
	s_mov_b64 s[10:11], s[70:71]
	s_mov_b64 s[12:13], s[68:69]
	s_mov_b64 s[8:9], s[22:23]
	s_cbranch_scc0 .LBB0_631
